# baseline (speedup 1.0000x reference)
; template <int MODE>
; __device__ __forceinline__ void attn_item(const Params& P, int b, int h, int qb, char* lds) {
;     ...
;         const float nref = -m_reg;
; #pragma unroll
;         for (int r = 0; r < 16; ++r) { p0[r] = nref; p1[r] = nref; }
;       }
;       {
;         const char* kbp = K_lds + buf * 16384;
; #pragma unroll
;         for (int d0 = 0; d0 < 8; ++d0) {
;           const char* a = kbp + KSWZ(r32, (d0 * 16 + hi * 8) * 2);
;           const bf16x8 b0 = *(const bf16x8*)a;
;           const bf16x8 b1 = *(const bf16x8*)(a + 32 * 256);
;           p0 = __builtin_amdgcn_mfma_f32_32x32x16_bf16(b0, qr[d0], p0, 0, 0, 0);
;           p1 = __builtin_amdgcn_mfma_f32_32x32x16_bf16(b1, qr[d0], p1, 0, 0, 0);
;         }
;       }
;       const float NEG = -__builtin_inff();
;       if (MODE == 0) {
;       } else {
;         if (kb + 63 > q0) {
;           const int dq = qpos - kb - 4 * hi;
; #pragma unroll
;           for (int r = 0; r < 16; ++r) {
;             const int c = (r & 3) + 8 * (r >> 2);
;             if (dq - c < 0) p0[r] = NEG;
;             if (dq - c - 32 < 0) p1[r] = NEG;
;           }
;         }
;       }
;       float pmax = p0[0];
; #pragma unroll
;       for (int r = 1; r < 16; ++r) pmax = fmaxf(pmax, p0[r]);
; #pragma unroll
;       for (int r = 0; r < 16; ++r) pmax = fmaxf(pmax, p1[r]);
;       pmax = fmaxf(pmax, __shfl_xor(pmax, 32));
;       if (!(started && __all(pmax < -160.f))) {
;       float alpha = 1.f;
;       if (!started || __any(pmax > 6.f)) {
.Lmy_pr_a:
	v_add_u32_e32 v0, s9, v182
	v_add_u32_e32 v6, v0, v183
	v_add_u32_e32 v10, v0, v181
	ds_read_b128 v[212:215], v6 offset:32768
	ds_read_b128 v[6:9], v6 offset:40960
	v_add_u32_e32 v187, v0, v179
	ds_read_b128 v[216:219], v10 offset:32768
	ds_read_b128 v[10:13], v10 offset:40960
	v_add_u32_e32 v2, v0, v178
	ds_read_b128 v[220:223], v187 offset:32768
	ds_read_b128 v[188:191], v187 offset:40960
	v_add_u32_e32 v196, v0, v177
	ds_read_b128 v[224:227], v2 offset:32768
	ds_read_b128 v[192:195], v2 offset:40960
	v_add_u32_e32 v3, v0, v176
	ds_read_b128 v[228:231], v196 offset:32768
	ds_read_b128 v[196:199], v196 offset:40960
	v_add_u32_e32 v204, v0, v175
	ds_read_b128 v[232:235], v3 offset:32768
	ds_read_b128 v[200:203], v3 offset:40960
	ds_read_b128 v[236:239], v204 offset:32768
	ds_read_b128 v[204:207], v204 offset:40960
	v_add_u32_e32 v0, v0, v174
	v_xor_b32_e32 v96, 0x80000000, v186
	v_mov_b32_e32 v97, v96
	v_mov_b64_e32 v[98:99], v[96:97]
	v_mov_b64_e32 v[100:101], v[96:97]
	v_mov_b64_e32 v[102:103], v[96:97]
	v_mov_b64_e32 v[104:105], v[96:97]
	v_mov_b64_e32 v[106:107], v[96:97]
	v_mov_b64_e32 v[108:109], v[96:97]
	v_mov_b64_e32 v[110:111], v[96:97]
	s_cmp_lg_u32 s0, 0
	s_waitcnt lgkmcnt(13)
	v_mfma_f32_32x32x16_bf16 v[112:127], v[212:215], v[156:159], v[96:111]
	ds_read_b128 v[240:243], v0 offset:32768
	ds_read_b128 v[208:211], v0 offset:40960
	s_waitcnt lgkmcnt(14)
	v_mfma_f32_32x32x16_bf16 v[96:111], v[6:9], v[156:159], v[96:111]
	s_waitcnt lgkmcnt(12)
	v_mfma_f32_32x32x16_bf16 v[112:127], v[216:219], v[152:155], v[112:127]
	v_mfma_f32_32x32x16_bf16 v[96:111], v[10:13], v[152:155], v[96:111]
	s_waitcnt lgkmcnt(10)
	v_mfma_f32_32x32x16_bf16 v[112:127], v[220:223], v[148:151], v[112:127]
	v_mfma_f32_32x32x16_bf16 v[96:111], v[188:191], v[148:151], v[96:111]
	s_waitcnt lgkmcnt(8)
	v_mfma_f32_32x32x16_bf16 v[112:127], v[224:227], v[144:147], v[112:127]
	v_mfma_f32_32x32x16_bf16 v[96:111], v[192:195], v[144:147], v[96:111]
	s_waitcnt lgkmcnt(6)
	v_mfma_f32_32x32x16_bf16 v[112:127], v[228:231], v[140:143], v[112:127]
	v_mfma_f32_32x32x16_bf16 v[96:111], v[196:199], v[140:143], v[96:111]
	s_waitcnt lgkmcnt(4)
	v_mfma_f32_32x32x16_bf16 v[112:127], v[232:235], v[136:139], v[112:127]
	v_mfma_f32_32x32x16_bf16 v[96:111], v[200:203], v[136:139], v[96:111]
	s_waitcnt lgkmcnt(2)
	v_mfma_f32_32x32x16_bf16 v[112:127], v[236:239], v[132:135], v[112:127]
	v_mfma_f32_32x32x16_bf16 v[96:111], v[204:207], v[132:135], v[96:111]
	s_waitcnt lgkmcnt(0)
	v_mfma_f32_32x32x16_bf16 v[112:127], v[240:243], v[128:131], v[112:127]
	v_mfma_f32_32x32x16_bf16 v[96:111], v[208:211], v[128:131], v[96:111]
	s_nop 10
	v_max_f32_e32 v0, v113, v113
	v_max_f32_e32 v2, v112, v112
	v_max_f32_e32 v0, v2, v0
	v_max3_f32 v0, v0, v114, v115
	v_max3_f32 v0, v0, v116, v117
	v_max3_f32 v0, v0, v118, v119
	v_max3_f32 v0, v0, v120, v121
	v_max3_f32 v0, v0, v122, v123
	v_max3_f32 v0, v0, v124, v125
	v_max3_f32 v0, v0, v126, v127
	v_max3_f32 v0, v0, v96, v97
	v_max3_f32 v0, v0, v98, v99
	v_max3_f32 v0, v0, v100, v101
	v_max3_f32 v0, v0, v102, v103
	v_max3_f32 v0, v0, v104, v105
	v_max3_f32 v0, v0, v106, v107
	v_max3_f32 v0, v0, v108, v109
	v_max3_f32 v0, v0, v110, v111
	v_mov_b32_e32 v2, v0
	s_nop 1
	v_permlane32_swap_b32_e32 v0, v2
	v_max_f32_e32 v0, v0, v2
	s_cbranch_scc0 .LBB0_689
	v_cmp_gt_f32_e32 vcc, s45, v0
	s_mov_b64 s[36:37], 0
	s_cmp_lg_u64 vcc, exec
	s_mov_b64 s[34:35], 0
	s_mov_b64 s[38:39], 0
	s_cbranch_scc0 .LBB0_690
	v_cmp_lt_f32_e32 vcc, s46, v0
	s_cbranch_vccz .Lmy_fast0
	v_max_f32_e32 v2, v0, v0
	v_max_f32_e32 v2, 0, v2
	s_mov_b64 s[38:39], -1
	s_and_b64 vcc, exec, s[36:37]
	s_cbranch_vccnz .LBB0_691
